# group barriers: last arriver skips the L2 write-back when the census says all members share one XCD (nx==1)
# speedup vs baseline: 1.0049x; 1.0049x over previous
; __device__ __forceinline__ unsigned xb_ld(unsigned* p)              { return __hip_atomic_load(p, __ATOMIC_RELAXED, __HIP_MEMORY_SCOPE_AGENT); }
; __device__ __forceinline__ unsigned xb_add(unsigned* p, unsigned v) { return __hip_atomic_fetch_add(p, v, __ATOMIC_RELAXED, __HIP_MEMORY_SCOPE_AGENT); }
; #define XB_SPIN(cond, bar) do { unsigned _sp = 0; while (cond) { __builtin_amdgcn_s_sleep(1); \
;     if ((++_sp & 255u) == 0u) { if (xb_ld(&(bar)[XB_TMO])) break; if (_sp > XB_SPIN_CAP) { atomicAdd(&(bar)[XB_TMO], 1u); break; } } } } while (0)
; __device__ __forceinline__ void xcd_barrier(const XcdBarrier& b) {
;     ...
;         const unsigned old = xb_add(&bar[XB_XSUB(b.x)], 1u);
;         const unsigned gen = old / nloc;
;         if (old + 1u == (gen + 1u) * nloc) {
;             __builtin_amdgcn_fence(__ATOMIC_RELEASE, "agent");
;             asm volatile("s_waitcnt vmcnt(0)" ::: "memory");
;             const unsigned og = xb_add(&bar[XB_TOP], 1u);
;             const unsigned tg = og / nx;
;             if (og + 1u == (tg + 1u) * nx) xb_add(&bar[XB_TOPGEN], 1u);
;             else XB_SPIN(xb_ld(&bar[XB_TOPGEN]) == tg, bar);
.LBB0_675:
	s_andn2_saveexec_b64 s[2:3], s[2:3]
	s_cbranch_execz .LBB0_691
	v_readlane_b32 s2, v252, 44
	v_cmp_eq_u32_e32 vcc, 1, v3
	s_cbranch_vccnz .Lgb_nowb0
	buffer_wbl2 sc1
.Lgb_nowb0:
	s_waitcnt lgkmcnt(0)
	s_waitcnt vmcnt(0)
	v_readlane_b32 s3, v252, 45
	v_cvt_f32_u32_e32 v4, v3
	v_sub_u32_e32 v5, 0, v3
	s_mov_b64 s[4:5], -1
	v_rcp_iflag_f32_e32 v4, v4
	s_nop 0
	global_atomic_add v2, v99, v215, s[2:3] sc0
	v_readlane_b32 s2, v252, 46
	v_readlane_b32 s3, v252, 47
	v_mul_f32_e32 v4, 0x4f7ffffe, v4
	v_cvt_u32_f32_e32 v4, v4
	v_mul_lo_u32 v5, v5, v4
	v_mul_hi_u32 v5, v4, v5
	v_add_u32_e32 v4, v4, v5
	s_waitcnt vmcnt(0)
	v_mul_hi_u32 v4, v2, v4
	v_mul_lo_u32 v5, v4, v3
	v_sub_u32_e32 v5, v2, v5
	v_cmp_ge_u32_e32 vcc, v5, v3
	v_add_u32_e32 v6, 1, v4
	v_add_u32_e32 v2, 1, v2
	v_cndmask_b32_e32 v4, v4, v6, vcc
	v_sub_u32_e32 v6, v5, v3
	v_cndmask_b32_e32 v5, v5, v6, vcc
	v_cmp_ge_u32_e32 vcc, v5, v3
	v_add_u32_e32 v5, 1, v4
	s_nop 0
	v_cndmask_b32_e32 v4, v4, v5, vcc
	v_mul_lo_u32 v5, v3, v4
	v_add_u32_e32 v3, v5, v3
	v_cmp_ne_u32_e32 vcc, v2, v3
	v_mov_b64_e32 v[2:3], s[2:3]
	s_and_saveexec_b64 s[2:3], vcc
	s_cbranch_execz .LBB0_688
	v_readlane_b32 s4, v252, 46
	v_readlane_b32 s5, v252, 47
	s_mov_b64 s[6:7], 0
	s_nop 3
	global_load_dword v2, v99, s[4:5] sc1
	s_waitcnt vmcnt(0)
	v_cmp_eq_u32_e32 vcc, v2, v4
	s_and_saveexec_b64 s[4:5], vcc
	s_cbranch_execz .LBB0_687
	s_mov_b32 s18, 1
	s_branch .LBB0_680

; __device__ __forceinline__ unsigned xb_ld(unsigned* p)              { return __hip_atomic_load(p, __ATOMIC_RELAXED, __HIP_MEMORY_SCOPE_AGENT); }
; __device__ __forceinline__ unsigned xb_add(unsigned* p, unsigned v) { return __hip_atomic_fetch_add(p, v, __ATOMIC_RELAXED, __HIP_MEMORY_SCOPE_AGENT); }
; #define XB_SPIN(cond, bar) do { unsigned _sp = 0; while (cond) { __builtin_amdgcn_s_sleep(1); \
;     if ((++_sp & 255u) == 0u) { if (xb_ld(&(bar)[XB_TMO])) break; if (_sp > XB_SPIN_CAP) { atomicAdd(&(bar)[XB_TMO], 1u); break; } } } } while (0)
; __device__ __forceinline__ void xcd_barrier(const XcdBarrier& b) {
;     ...
;         const unsigned old = xb_add(&bar[XB_XSUB(b.x)], 1u);
;         const unsigned gen = old / nloc;
;         if (old + 1u == (gen + 1u) * nloc) {
;             __builtin_amdgcn_fence(__ATOMIC_RELEASE, "agent");
;             asm volatile("s_waitcnt vmcnt(0)" ::: "memory");
;             const unsigned og = xb_add(&bar[XB_TOP], 1u);
;             const unsigned tg = og / nx;
;             if (og + 1u == (tg + 1u) * nx) xb_add(&bar[XB_TOPGEN], 1u);
;             else XB_SPIN(xb_ld(&bar[XB_TOPGEN]) == tg, bar);
.Lgb_nowb4:
	s_waitcnt lgkmcnt(0)
	s_waitcnt vmcnt(0)
	v_readlane_b32 s3, v252, 45
	v_cvt_f32_u32_e32 v4, v3
	v_sub_u32_e32 v5, 0, v3
	s_mov_b64 s[4:5], -1
	v_rcp_iflag_f32_e32 v4, v4
	s_nop 0
	global_atomic_add v2, v99, v215, s[2:3] sc0
	v_readlane_b32 s2, v252, 46
	v_readlane_b32 s3, v252, 47
	v_mul_f32_e32 v4, 0x4f7ffffe, v4
	v_cvt_u32_f32_e32 v4, v4
	v_mul_lo_u32 v5, v5, v4
	v_mul_hi_u32 v5, v4, v5
	v_add_u32_e32 v4, v4, v5
	s_waitcnt vmcnt(0)
	v_mul_hi_u32 v4, v2, v4
	v_mul_lo_u32 v5, v4, v3
	v_sub_u32_e32 v5, v2, v5
	v_cmp_ge_u32_e32 vcc, v5, v3
	v_add_u32_e32 v6, 1, v4
	v_add_u32_e32 v2, 1, v2
	v_cndmask_b32_e32 v4, v4, v6, vcc
	v_sub_u32_e32 v6, v5, v3
	v_cndmask_b32_e32 v5, v5, v6, vcc
	v_cmp_ge_u32_e32 vcc, v5, v3
	v_add_u32_e32 v5, 1, v4
	s_nop 0
	v_cndmask_b32_e32 v4, v4, v5, vcc
	v_mul_lo_u32 v5, v3, v4
	v_add_u32_e32 v3, v5, v3
	v_cmp_ne_u32_e32 vcc, v2, v3
	v_mov_b64_e32 v[2:3], s[2:3]
	s_and_saveexec_b64 s[2:3], vcc
	s_cbranch_execz .LBB0_1097
	v_readlane_b32 s4, v252, 46
	v_readlane_b32 s5, v252, 47
	s_mov_b64 s[8:9], 0
	s_nop 3
	global_load_dword v2, v99, s[4:5] sc1
	s_waitcnt vmcnt(0)
	v_cmp_eq_u32_e32 vcc, v2, v4
	s_and_saveexec_b64 s[4:5], vcc
	s_cbranch_execz .LBB0_1096
	s_mov_b32 s10, 1
	s_branch .LBB0_1089

; __device__ __forceinline__ unsigned xb_ld(unsigned* p)              { return __hip_atomic_load(p, __ATOMIC_RELAXED, __HIP_MEMORY_SCOPE_AGENT); }
; __device__ __forceinline__ unsigned xb_add(unsigned* p, unsigned v) { return __hip_atomic_fetch_add(p, v, __ATOMIC_RELAXED, __HIP_MEMORY_SCOPE_AGENT); }
; #define XB_SPIN(cond, bar) do { unsigned _sp = 0; while (cond) { __builtin_amdgcn_s_sleep(1); \
;     if ((++_sp & 255u) == 0u) { if (xb_ld(&(bar)[XB_TMO])) break; if (_sp > XB_SPIN_CAP) { atomicAdd(&(bar)[XB_TMO], 1u); break; } } } } while (0)
; __device__ __forceinline__ void xcd_barrier(const XcdBarrier& b) {
;     ...
;         const unsigned old = xb_add(&bar[XB_XSUB(b.x)], 1u);
;         const unsigned gen = old / nloc;
;         if (old + 1u == (gen + 1u) * nloc) {
;             __builtin_amdgcn_fence(__ATOMIC_RELEASE, "agent");
;             asm volatile("s_waitcnt vmcnt(0)" ::: "memory");
;             const unsigned og = xb_add(&bar[XB_TOP], 1u);
;             const unsigned tg = og / nx;
;             if (og + 1u == (tg + 1u) * nx) xb_add(&bar[XB_TOPGEN], 1u);
;             else XB_SPIN(xb_ld(&bar[XB_TOPGEN]) == tg, bar);
.LBB0_1131:
	s_andn2_saveexec_b64 s[4:5], s[4:5]
	s_cbranch_execz .LBB0_1147
	v_readlane_b32 s4, v252, 44
	v_cmp_eq_u32_e32 vcc, 1, v3
	s_cbranch_vccnz .Lgb_nowb5
	buffer_wbl2 sc1
.Lgb_nowb5:
	s_waitcnt lgkmcnt(0)
	s_waitcnt vmcnt(0)
	v_readlane_b32 s5, v252, 45
	v_cvt_f32_u32_e32 v4, v3
	v_sub_u32_e32 v5, 0, v3
	s_mov_b64 s[6:7], -1
	v_rcp_iflag_f32_e32 v4, v4
	s_nop 0
	global_atomic_add v2, v99, v215, s[4:5] sc0
	v_readlane_b32 s4, v252, 46
	v_readlane_b32 s5, v252, 47
	v_mul_f32_e32 v4, 0x4f7ffffe, v4
	v_cvt_u32_f32_e32 v4, v4
	v_mul_lo_u32 v5, v5, v4
	v_mul_hi_u32 v5, v4, v5
	v_add_u32_e32 v4, v4, v5
	s_waitcnt vmcnt(0)
	v_mul_hi_u32 v4, v2, v4
	v_mul_lo_u32 v5, v4, v3
	v_sub_u32_e32 v5, v2, v5
	v_cmp_ge_u32_e32 vcc, v5, v3
	v_add_u32_e32 v6, 1, v4
	v_add_u32_e32 v2, 1, v2
	v_cndmask_b32_e32 v4, v4, v6, vcc
	v_sub_u32_e32 v6, v5, v3
	v_cndmask_b32_e32 v5, v5, v6, vcc
	v_cmp_ge_u32_e32 vcc, v5, v3
	v_add_u32_e32 v5, 1, v4
	s_nop 0
	v_cndmask_b32_e32 v4, v4, v5, vcc
	v_mul_lo_u32 v5, v3, v4
	v_add_u32_e32 v3, v5, v3
	v_cmp_ne_u32_e32 vcc, v2, v3
	v_mov_b64_e32 v[2:3], s[4:5]
	s_and_saveexec_b64 s[4:5], vcc
	s_cbranch_execz .LBB0_1144
	v_readlane_b32 s6, v252, 46
	v_readlane_b32 s7, v252, 47
	s_mov_b64 s[8:9], 0
	s_nop 3
	global_load_dword v2, v99, s[6:7] sc1
	s_waitcnt vmcnt(0)
	v_cmp_eq_u32_e32 vcc, v2, v4
	s_and_saveexec_b64 s[6:7], vcc
	s_cbranch_execz .LBB0_1143
	s_mov_b32 s20, 1
	s_branch .LBB0_1136
